# pool_conv trailing-window prefix: 16 predicated loads issued together instead of one memory round trip per element
# speedup vs baseline: 1.0113x; 1.0017x over previous
.LBB0_767:
	v_mad_i64_i32 v[18:19], s[4:5], v31, s3, v[14:15]
	v_lshl_add_u32 v16, s19, 6, v17
	v_and_b32_e32 v1, 0x1fe0, v16
	s_mov_b64 s[4:5], 0
	s_mov_b32 s6, s7
	v_mov_b32_e32 v23, 0
	v_min_u32_e32 v120, v1, v28
	v_mov_b32_e32 v121, 0
	v_mov_b32_e32 v122, 0
	v_mov_b32_e32 v123, 0
	v_mov_b32_e32 v124, 0
	v_mov_b32_e32 v125, 0
	v_mov_b32_e32 v126, 0
	v_mov_b32_e32 v127, 0
	v_mov_b32_e32 v128, 0
	v_mov_b32_e32 v129, 0
	v_mov_b32_e32 v130, 0
	v_mov_b32_e32 v131, 0
	v_mov_b32_e32 v132, 0
	v_mov_b32_e32 v133, 0
	v_mov_b32_e32 v134, 0
	v_mov_b32_e32 v135, 0
	v_mov_b32_e32 v136, 0
	v_cmp_le_u32_e32 vcc, 1, v120
	s_and_saveexec_b64 s[16:17], vcc
	global_load_ushort v121, v[18:19], off
	s_mov_b64 exec, s[16:17]
	v_lshl_add_u64 v[18:19], v[18:19], 0, s[10:11]
	v_cmp_le_u32_e32 vcc, 2, v120
	s_and_saveexec_b64 s[16:17], vcc
	global_load_ushort v122, v[18:19], off
	s_mov_b64 exec, s[16:17]
	v_lshl_add_u64 v[18:19], v[18:19], 0, s[10:11]
	v_cmp_le_u32_e32 vcc, 3, v120
	s_and_saveexec_b64 s[16:17], vcc
	global_load_ushort v123, v[18:19], off
	s_mov_b64 exec, s[16:17]
	v_lshl_add_u64 v[18:19], v[18:19], 0, s[10:11]
	v_cmp_le_u32_e32 vcc, 4, v120
	s_and_saveexec_b64 s[16:17], vcc
	global_load_ushort v124, v[18:19], off
	s_mov_b64 exec, s[16:17]
	v_lshl_add_u64 v[18:19], v[18:19], 0, s[10:11]
	v_cmp_le_u32_e32 vcc, 5, v120
	s_and_saveexec_b64 s[16:17], vcc
	global_load_ushort v125, v[18:19], off
	s_mov_b64 exec, s[16:17]
	v_lshl_add_u64 v[18:19], v[18:19], 0, s[10:11]
	v_cmp_le_u32_e32 vcc, 6, v120
	s_and_saveexec_b64 s[16:17], vcc
	global_load_ushort v126, v[18:19], off
	s_mov_b64 exec, s[16:17]
	v_lshl_add_u64 v[18:19], v[18:19], 0, s[10:11]
	v_cmp_le_u32_e32 vcc, 7, v120
	s_and_saveexec_b64 s[16:17], vcc
	global_load_ushort v127, v[18:19], off
	s_mov_b64 exec, s[16:17]
	v_lshl_add_u64 v[18:19], v[18:19], 0, s[10:11]
	v_cmp_le_u32_e32 vcc, 8, v120
	s_and_saveexec_b64 s[16:17], vcc
	global_load_ushort v128, v[18:19], off
	s_mov_b64 exec, s[16:17]
	v_lshl_add_u64 v[18:19], v[18:19], 0, s[10:11]
	v_cmp_le_u32_e32 vcc, 9, v120
	s_and_saveexec_b64 s[16:17], vcc
	global_load_ushort v129, v[18:19], off
	s_mov_b64 exec, s[16:17]
	v_lshl_add_u64 v[18:19], v[18:19], 0, s[10:11]
	v_cmp_le_u32_e32 vcc, 10, v120
	s_and_saveexec_b64 s[16:17], vcc
	global_load_ushort v130, v[18:19], off
	s_mov_b64 exec, s[16:17]
	v_lshl_add_u64 v[18:19], v[18:19], 0, s[10:11]
	v_cmp_le_u32_e32 vcc, 11, v120
	s_and_saveexec_b64 s[16:17], vcc
	global_load_ushort v131, v[18:19], off
	s_mov_b64 exec, s[16:17]
	v_lshl_add_u64 v[18:19], v[18:19], 0, s[10:11]
	v_cmp_le_u32_e32 vcc, 12, v120
	s_and_saveexec_b64 s[16:17], vcc
	global_load_ushort v132, v[18:19], off
	s_mov_b64 exec, s[16:17]
	v_lshl_add_u64 v[18:19], v[18:19], 0, s[10:11]
	v_cmp_le_u32_e32 vcc, 13, v120
	s_and_saveexec_b64 s[16:17], vcc
	global_load_ushort v133, v[18:19], off
	s_mov_b64 exec, s[16:17]
	v_lshl_add_u64 v[18:19], v[18:19], 0, s[10:11]
	v_cmp_le_u32_e32 vcc, 14, v120
	s_and_saveexec_b64 s[16:17], vcc
	global_load_ushort v134, v[18:19], off
	s_mov_b64 exec, s[16:17]
	v_lshl_add_u64 v[18:19], v[18:19], 0, s[10:11]
	v_cmp_le_u32_e32 vcc, 15, v120
	s_and_saveexec_b64 s[16:17], vcc
	global_load_ushort v135, v[18:19], off
	s_mov_b64 exec, s[16:17]
	v_lshl_add_u64 v[18:19], v[18:19], 0, s[10:11]
	v_cmp_le_u32_e32 vcc, 16, v120
	s_and_saveexec_b64 s[16:17], vcc
	global_load_ushort v136, v[18:19], off
	s_mov_b64 exec, s[16:17]
	v_lshl_add_u64 v[18:19], v[18:19], 0, s[10:11]
	s_waitcnt vmcnt(0)
	v_cvt_f32_f16_e32 v121, v121
	v_add_f32_e32 v23, v23, v121
	v_cvt_f32_f16_e32 v122, v122
	v_add_f32_e32 v23, v23, v122
	v_cvt_f32_f16_e32 v123, v123
	v_add_f32_e32 v23, v23, v123
	v_cvt_f32_f16_e32 v124, v124
	v_add_f32_e32 v23, v23, v124
	v_cvt_f32_f16_e32 v125, v125
	v_add_f32_e32 v23, v23, v125
	v_cvt_f32_f16_e32 v126, v126
	v_add_f32_e32 v23, v23, v126
	v_cvt_f32_f16_e32 v127, v127
	v_add_f32_e32 v23, v23, v127
	v_cvt_f32_f16_e32 v128, v128
	v_add_f32_e32 v23, v23, v128
	v_cvt_f32_f16_e32 v129, v129
	v_add_f32_e32 v23, v23, v129
	v_cvt_f32_f16_e32 v130, v130
	v_add_f32_e32 v23, v23, v130
	v_cvt_f32_f16_e32 v131, v131
	v_add_f32_e32 v23, v23, v131
	v_cvt_f32_f16_e32 v132, v132
	v_add_f32_e32 v23, v23, v132
	v_cvt_f32_f16_e32 v133, v133
	v_add_f32_e32 v23, v23, v133
	v_cvt_f32_f16_e32 v134, v134
	v_add_f32_e32 v23, v23, v134
	v_cvt_f32_f16_e32 v135, v135
	v_add_f32_e32 v23, v23, v135
	v_cvt_f32_f16_e32 v136, v136
	v_add_f32_e32 v23, v23, v136
	v_mad_i64_i32 v[18:19], s[4:5], v16, s3, v[12:13]
	s_mov_b32 s20, 0
	s_mov_b64 s[16:17], -1
	s_branch .LBB0_773

.LBB0_2476:
	v_mad_i64_i32 v[22:23], s[4:5], v35, s3, v[18:19]
	v_lshl_add_u32 v20, s19, 6, v21
	v_and_b32_e32 v1, 0x1fe0, v20
	s_mov_b64 s[4:5], 0
	s_mov_b32 s6, s7
	v_mov_b32_e32 v27, 0
	v_min_u32_e32 v120, v1, v32
	v_mov_b32_e32 v121, 0
	v_mov_b32_e32 v122, 0
	v_mov_b32_e32 v123, 0
	v_mov_b32_e32 v124, 0
	v_mov_b32_e32 v125, 0
	v_mov_b32_e32 v126, 0
	v_mov_b32_e32 v127, 0
	v_mov_b32_e32 v128, 0
	v_mov_b32_e32 v129, 0
	v_mov_b32_e32 v130, 0
	v_mov_b32_e32 v131, 0
	v_mov_b32_e32 v132, 0
	v_mov_b32_e32 v133, 0
	v_mov_b32_e32 v134, 0
	v_mov_b32_e32 v135, 0
	v_mov_b32_e32 v136, 0
	v_cmp_le_u32_e32 vcc, 1, v120
	s_and_saveexec_b64 s[16:17], vcc
	global_load_ushort v121, v[22:23], off
	s_mov_b64 exec, s[16:17]
	v_lshl_add_u64 v[22:23], v[22:23], 0, s[10:11]
	v_cmp_le_u32_e32 vcc, 2, v120
	s_and_saveexec_b64 s[16:17], vcc
	global_load_ushort v122, v[22:23], off
	s_mov_b64 exec, s[16:17]
	v_lshl_add_u64 v[22:23], v[22:23], 0, s[10:11]
	v_cmp_le_u32_e32 vcc, 3, v120
	s_and_saveexec_b64 s[16:17], vcc
	global_load_ushort v123, v[22:23], off
	s_mov_b64 exec, s[16:17]
	v_lshl_add_u64 v[22:23], v[22:23], 0, s[10:11]
	v_cmp_le_u32_e32 vcc, 4, v120
	s_and_saveexec_b64 s[16:17], vcc
	global_load_ushort v124, v[22:23], off
	s_mov_b64 exec, s[16:17]
	v_lshl_add_u64 v[22:23], v[22:23], 0, s[10:11]
	v_cmp_le_u32_e32 vcc, 5, v120
	s_and_saveexec_b64 s[16:17], vcc
	global_load_ushort v125, v[22:23], off
	s_mov_b64 exec, s[16:17]
	v_lshl_add_u64 v[22:23], v[22:23], 0, s[10:11]
	v_cmp_le_u32_e32 vcc, 6, v120
	s_and_saveexec_b64 s[16:17], vcc
	global_load_ushort v126, v[22:23], off
	s_mov_b64 exec, s[16:17]
	v_lshl_add_u64 v[22:23], v[22:23], 0, s[10:11]
	v_cmp_le_u32_e32 vcc, 7, v120
	s_and_saveexec_b64 s[16:17], vcc
	global_load_ushort v127, v[22:23], off
	s_mov_b64 exec, s[16:17]
	v_lshl_add_u64 v[22:23], v[22:23], 0, s[10:11]
	v_cmp_le_u32_e32 vcc, 8, v120
	s_and_saveexec_b64 s[16:17], vcc
	global_load_ushort v128, v[22:23], off
	s_mov_b64 exec, s[16:17]
	v_lshl_add_u64 v[22:23], v[22:23], 0, s[10:11]
	v_cmp_le_u32_e32 vcc, 9, v120
	s_and_saveexec_b64 s[16:17], vcc
	global_load_ushort v129, v[22:23], off
	s_mov_b64 exec, s[16:17]
	v_lshl_add_u64 v[22:23], v[22:23], 0, s[10:11]
	v_cmp_le_u32_e32 vcc, 10, v120
	s_and_saveexec_b64 s[16:17], vcc
	global_load_ushort v130, v[22:23], off
	s_mov_b64 exec, s[16:17]
	v_lshl_add_u64 v[22:23], v[22:23], 0, s[10:11]
	v_cmp_le_u32_e32 vcc, 11, v120
	s_and_saveexec_b64 s[16:17], vcc
	global_load_ushort v131, v[22:23], off
	s_mov_b64 exec, s[16:17]
	v_lshl_add_u64 v[22:23], v[22:23], 0, s[10:11]
	v_cmp_le_u32_e32 vcc, 12, v120
	s_and_saveexec_b64 s[16:17], vcc
	global_load_ushort v132, v[22:23], off
	s_mov_b64 exec, s[16:17]
	v_lshl_add_u64 v[22:23], v[22:23], 0, s[10:11]
	v_cmp_le_u32_e32 vcc, 13, v120
	s_and_saveexec_b64 s[16:17], vcc
	global_load_ushort v133, v[22:23], off
	s_mov_b64 exec, s[16:17]
	v_lshl_add_u64 v[22:23], v[22:23], 0, s[10:11]
	v_cmp_le_u32_e32 vcc, 14, v120
	s_and_saveexec_b64 s[16:17], vcc
	global_load_ushort v134, v[22:23], off
	s_mov_b64 exec, s[16:17]
	v_lshl_add_u64 v[22:23], v[22:23], 0, s[10:11]
	v_cmp_le_u32_e32 vcc, 15, v120
	s_and_saveexec_b64 s[16:17], vcc
	global_load_ushort v135, v[22:23], off
	s_mov_b64 exec, s[16:17]
	v_lshl_add_u64 v[22:23], v[22:23], 0, s[10:11]
	v_cmp_le_u32_e32 vcc, 16, v120
	s_and_saveexec_b64 s[16:17], vcc
	global_load_ushort v136, v[22:23], off
	s_mov_b64 exec, s[16:17]
	v_lshl_add_u64 v[22:23], v[22:23], 0, s[10:11]
	s_waitcnt vmcnt(0)
	v_cvt_f32_f16_e32 v121, v121
	v_add_f32_e32 v27, v27, v121
	v_cvt_f32_f16_e32 v122, v122
	v_add_f32_e32 v27, v27, v122
	v_cvt_f32_f16_e32 v123, v123
	v_add_f32_e32 v27, v27, v123
	v_cvt_f32_f16_e32 v124, v124
	v_add_f32_e32 v27, v27, v124
	v_cvt_f32_f16_e32 v125, v125
	v_add_f32_e32 v27, v27, v125
	v_cvt_f32_f16_e32 v126, v126
	v_add_f32_e32 v27, v27, v126
	v_cvt_f32_f16_e32 v127, v127
	v_add_f32_e32 v27, v27, v127
	v_cvt_f32_f16_e32 v128, v128
	v_add_f32_e32 v27, v27, v128
	v_cvt_f32_f16_e32 v129, v129
	v_add_f32_e32 v27, v27, v129
	v_cvt_f32_f16_e32 v130, v130
	v_add_f32_e32 v27, v27, v130
	v_cvt_f32_f16_e32 v131, v131
	v_add_f32_e32 v27, v27, v131
	v_cvt_f32_f16_e32 v132, v132
	v_add_f32_e32 v27, v27, v132
	v_cvt_f32_f16_e32 v133, v133
	v_add_f32_e32 v27, v27, v133
	v_cvt_f32_f16_e32 v134, v134
	v_add_f32_e32 v27, v27, v134
	v_cvt_f32_f16_e32 v135, v135
	v_add_f32_e32 v27, v27, v135
	v_cvt_f32_f16_e32 v136, v136
	v_add_f32_e32 v27, v27, v136
	v_mad_i64_i32 v[22:23], s[4:5], v20, s3, v[16:17]
	s_mov_b32 s20, 0
	s_mov_b64 s[16:17], -1
	s_branch .LBB0_2482
